# st7 row loop software-pipelined: next row's loads issued one iteration ahead into second register set, counted vmcnt
# speedup vs baseline: 1.0100x; 1.0025x over previous
; __global__ void __launch_bounds__(512, 2) fwd_megakernel(Params P) {
;     ...
;                 for (int it = gw; it < 2048; it += NGW) {
;                     const int ms = (it >> 1) * 32, c0 = (it & 1) * 512 + lane * 8, head = c0 >> 6;
;                     float lnw[8], lnb[8]; ldf8(kp->in[I_LNW] + (size_t)L * 1024 + c0, lnw); ldf8(kp->in[I_LNB] + (size_t)L * 1024 + c0, lnb);
; #pragma unroll 2
;                     for (int m = ms; m < ms + 32; ++m) {
;                         const size_t o = (size_t)m * 1024 + c0;
;                         float y[8], v[8], g[8], out[8]; ld8nt(Y16 + o, y); ld8nt(SI + ARR + o, v); ld8nt(Zg + o, g);
.LBB0_125:
	s_and_b32 s18, s3, 0xffffffe0
	s_ashr_i32 s19, s18, 31
	s_add_i32 s17, s18, -1
	s_lshl_b64 s[20:21], s[18:19], 12
	s_add_u32 s20, s20, 0x3000000
	s_addc_u32 s21, s21, 0
	s_and_b32 s22, s9, 0x200
	v_or_b32_e32 v8, s22, v31
	v_lshlrev_b32_e32 v9, 1, v8
	v_or_b32_e32 v2, s20, v9
	v_mov_b32_e32 v3, s21
	s_lshl_b64 s[20:21], s[18:19], 6
	s_add_u32 s20, s20, 0x2d40000
	s_addc_u32 s21, s21, 0
	s_lshl_b64 s[18:19], s[18:19], 11
	v_mov_b32_e32 v27, s19
	s_lshl_b32 s19, s16, 9
	v_lshrrev_b32_e32 v8, 4, v8
	s_and_b32 s19, s19, 0x200
	v_and_or_b32 v24, v8, 60, s20
	v_or_b32_e32 v8, s19, v31
	v_lshlrev_b32_e32 v20, 2, v8
	v_or_b32_e32 v26, s18, v9
	global_load_dwordx4 v[8:11], v20, s[12:13]
	global_load_dwordx4 v[12:15], v20, s[12:13] offset:16
	global_load_dwordx4 v[16:19], v20, s[14:15]
	s_nop 0
	global_load_dwordx4 v[20:23], v20, s[14:15] offset:16
	s_lshl_b32 s18, s16, 4
	v_mov_b32_e32 v25, s21
	s_or_b32 s18, s18, 31
	v_lshl_add_u64 v[86:87], s[6:7], 0, v[26:27]
	v_add_co_u32_e32 v88, vcc, 0x24000000, v86
	v_lshl_add_u64 v[92:93], s[6:7], 0, v[24:25]
	s_nop 0
	v_addc_co_u32_e32 v89, vcc, 0, v87, vcc
	v_add_co_u32_e32 v90, vcc, 0x28000000, v86
	global_load_dwordx4 v[72:75], v[88:89], off nt
	s_nop 0
	v_addc_co_u32_e32 v91, vcc, 0, v87, vcc
	v_add_co_u32_e32 v86, vcc, 0x17000000, v86
	global_load_dwordx4 v[76:79], v[90:91], off nt
	s_nop 0
	v_addc_co_u32_e32 v87, vcc, 0, v87, vcc
	global_load_dwordx4 v[80:83], v[86:87], off nt
	global_load_dword v84, v[92:93], off
	global_load_dword v85, v[92:93], off
; __device__ __forceinline__ float sigm(float x) { return __builtin_amdgcn_rcpf(1.0f + __expf(-x)); }
; __device__ __forceinline__ float sum8(float x) { x += dppf<0xB1>(x); x += dppf<0x4E>(x); x += dppf<0x141>(x); return x; }
; __device__ __forceinline__ void st8(f16* p, const float (&v)[8]) { u32x4 w; w.x = pkh(v[0], v[1]); w.y = pkh(v[2], v[3]); w.z = pkh(v[4], v[5]); w.w = pkh(v[6], v[7]); *(u32x4*)p = w; }
; __global__ void __launch_bounds__(512, 2) fwd_megakernel(Params P) {
;     ...
;                     for (int m = ms; m < ms + 32; ++m) {
;                         const size_t o = (size_t)m * 1024 + c0;
;                         float y[8], v[8], g[8], out[8]; ld8nt(Y16 + o, y); ld8nt(SI + ARR + o, v); ld8nt(Zg + o, g);
;                         const float bs = BS[(size_t)m * 16 + head];
;                         float s = 0.f;
; #pragma unroll
;                         for (int i = 0; i < 8; ++i) s += y[i];
;                         const float mean = sum8(s) * (1.0f / 64.0f); float q = 0.f;
; #pragma unroll
;                         for (int i = 0; i < 8; ++i) { y[i] -= mean; q += y[i] * y[i]; }
;                         const float rstd = __builtin_amdgcn_rsqf(sum8(q) * (1.0f / 64.0f) + 64e-5f);
; #pragma unroll
;                         for (int i = 0; i < 8; ++i) out[i] = (y[i] * rstd * lnw[i] + lnb[i] + bs * v[i]) * g[i] * sigm(g[i]);
;                         st8(BUFA + (size_t)m * 2048 + c0, out);
;                     }
.LBB0_126:
	s_add_i32 s17, s17, 1
	v_lshl_add_u64 v[28:29], s[6:7], 0, v[2:3]
	v_lshl_add_u64 v[2:3], v[2:3], 0, s[56:57]
	v_lshl_add_u64 v[24:25], v[24:25], 0, 64
	v_lshl_add_u64 v[26:27], v[26:27], 0, s[84:85]
	s_cmp_ge_i32 s17, s18
	s_waitcnt vmcnt(4)
	v_cvt_f32_f16_e32 v62, v72
	v_cvt_f32_f16_sdwa v63, v72 dst_sel:DWORD dst_unused:UNUSED_PAD src0_sel:WORD_1
	v_cvt_f32_f16_e32 v56, v75
	v_cvt_f32_f16_sdwa v57, v75 dst_sel:DWORD dst_unused:UNUSED_PAD src0_sel:WORD_1
	v_cvt_f32_f16_e32 v58, v74
	v_cvt_f32_f16_sdwa v59, v74 dst_sel:DWORD dst_unused:UNUSED_PAD src0_sel:WORD_1
	v_cvt_f32_f16_e32 v60, v73
	v_cvt_f32_f16_sdwa v61, v73 dst_sel:DWORD dst_unused:UNUSED_PAD src0_sel:WORD_1
	s_waitcnt vmcnt(3)
	v_cvt_f32_f16_e32 v32, v79
	v_cvt_f32_f16_sdwa v33, v79 dst_sel:DWORD dst_unused:UNUSED_PAD src0_sel:WORD_1
	v_cvt_f32_f16_e32 v34, v78
	v_cvt_f32_f16_sdwa v35, v78 dst_sel:DWORD dst_unused:UNUSED_PAD src0_sel:WORD_1
	v_cvt_f32_f16_e32 v38, v77
	v_cvt_f32_f16_sdwa v39, v77 dst_sel:DWORD dst_unused:UNUSED_PAD src0_sel:WORD_1
	v_cvt_f32_f16_e32 v42, v76
	v_cvt_f32_f16_sdwa v43, v76 dst_sel:DWORD dst_unused:UNUSED_PAD src0_sel:WORD_1
	s_waitcnt vmcnt(2)
	v_cvt_f32_f16_e32 v36, v83
	v_cvt_f32_f16_sdwa v37, v83 dst_sel:DWORD dst_unused:UNUSED_PAD src0_sel:WORD_1
	v_cvt_f32_f16_e32 v40, v82
	v_cvt_f32_f16_sdwa v41, v82 dst_sel:DWORD dst_unused:UNUSED_PAD src0_sel:WORD_1
	v_cvt_f32_f16_e32 v44, v81
	v_cvt_f32_f16_sdwa v45, v81 dst_sel:DWORD dst_unused:UNUSED_PAD src0_sel:WORD_1
	v_cvt_f32_f16_e32 v46, v80
	v_cvt_f32_f16_sdwa v47, v80 dst_sel:DWORD dst_unused:UNUSED_PAD src0_sel:WORD_1
	v_lshl_add_u64 v[86:87], s[6:7], 0, v[26:27]
	v_add_co_u32_e32 v88, vcc, 0x24000000, v86
	v_lshl_add_u64 v[92:93], s[6:7], 0, v[24:25]
	s_nop 0
	v_addc_co_u32_e32 v89, vcc, 0, v87, vcc
	v_add_co_u32_e32 v90, vcc, 0x28000000, v86
	global_load_dwordx4 v[72:75], v[88:89], off nt
	s_nop 0
	v_addc_co_u32_e32 v91, vcc, 0, v87, vcc
	v_add_co_u32_e32 v86, vcc, 0x17000000, v86
	global_load_dwordx4 v[76:79], v[90:91], off nt
	s_nop 0
	v_addc_co_u32_e32 v87, vcc, 0, v87, vcc
	global_load_dwordx4 v[80:83], v[86:87], off nt
	v_add_f32_e32 v48, 0, v62
	v_add_f32_e32 v48, v48, v63
	v_mul_f32_e32 v49, 0xbfb8aa3b, v36
	v_mul_f32_e32 v50, 0xbfb8aa3b, v37
	v_mul_f32_e32 v51, 0xbfb8aa3b, v40
	v_mul_f32_e32 v52, 0xbfb8aa3b, v41
	v_mul_f32_e32 v53, 0xbfb8aa3b, v44
	v_mul_f32_e32 v54, 0xbfb8aa3b, v45
	v_mul_f32_e32 v55, 0xbfb8aa3b, v46
	v_mul_f32_e32 v64, 0xbfb8aa3b, v47
	v_add_f32_e32 v48, v48, v60
	v_exp_f32_e32 v49, v49
	v_exp_f32_e32 v50, v50
	v_exp_f32_e32 v51, v51
	v_exp_f32_e32 v52, v52
	v_exp_f32_e32 v53, v53
	v_exp_f32_e32 v54, v54
	v_exp_f32_e32 v55, v55
	v_exp_f32_e32 v64, v64
	v_add_f32_e32 v48, v48, v61
	v_add_f32_e32 v48, v48, v58
	v_add_f32_e32 v48, v48, v59
	v_add_f32_e32 v48, v48, v56
	v_add_f32_e32 v49, 1.0, v49
	v_add_f32_e32 v50, 1.0, v50
	v_add_f32_e32 v51, 1.0, v51
	v_add_f32_e32 v52, 1.0, v52
	v_add_f32_e32 v53, 1.0, v53
	v_add_f32_e32 v54, 1.0, v54
	v_add_f32_e32 v55, 1.0, v55
	v_add_f32_e32 v64, 1.0, v64
	v_add_f32_e32 v65, v48, v57
	v_rcp_f32_e32 v48, v49
	v_rcp_f32_e32 v49, v50
	v_rcp_f32_e32 v50, v51
	v_rcp_f32_e32 v51, v52
	v_rcp_f32_e32 v52, v53
	v_rcp_f32_e32 v53, v54
	v_rcp_f32_e32 v54, v55
	v_rcp_f32_e32 v55, v64
	v_add_f32_dpp v64, v65, v65 quad_perm:[1,0,3,2] row_mask:0xf bank_mask:0xf bound_ctrl:1
	s_nop 1
	v_add_f32_dpp v64, v64, v64 quad_perm:[2,3,0,1] row_mask:0xf bank_mask:0xf bound_ctrl:1
	s_nop 1
	v_add_f32_dpp v64, v64, v64 row_half_mirror row_mask:0xf bank_mask:0xf bound_ctrl:1
	v_mul_f32_e32 v64, 0x3c800000, v64
	v_pk_add_f32 v[62:63], v[62:63], v[64:65] op_sel_hi:[1,0] neg_lo:[0,1] neg_hi:[0,1]
	v_pk_add_f32 v[60:61], v[60:61], v[64:65] op_sel_hi:[1,0] neg_lo:[0,1] neg_hi:[0,1]
	v_pk_add_f32 v[58:59], v[58:59], v[64:65] op_sel_hi:[1,0] neg_lo:[0,1] neg_hi:[0,1]
	v_pk_add_f32 v[56:57], v[56:57], v[64:65] op_sel_hi:[1,0] neg_lo:[0,1] neg_hi:[0,1]
	v_pk_mul_f32 v[64:65], v[62:63], v[62:63]
	v_pk_mul_f32 v[66:67], v[60:61], v[60:61]
	v_add_f32_e32 v64, v64, v65
	v_add_f32_e32 v64, v64, v66
	v_pk_mul_f32 v[68:69], v[58:59], v[58:59]
	v_add_f32_e32 v64, v64, v67
	v_add_f32_e32 v64, v64, v68
	v_pk_mul_f32 v[70:71], v[56:57], v[56:57]
	v_add_f32_e32 v64, v64, v69
	v_add_f32_e32 v64, v64, v70
	v_add_f32_e32 v64, v64, v71
	v_mov_b32_e32 v65, 0x3a27c5ac
	s_nop 0
	v_add_f32_dpp v64, v64, v64 quad_perm:[1,0,3,2] row_mask:0xf bank_mask:0xf bound_ctrl:1
	s_nop 1
	v_add_f32_dpp v64, v64, v64 quad_perm:[2,3,0,1] row_mask:0xf bank_mask:0xf bound_ctrl:1
	s_nop 1
	v_add_f32_dpp v64, v64, v64 row_half_mirror row_mask:0xf bank_mask:0xf bound_ctrl:1
	v_fmamk_f32 v64, v64, 0x3c800000, v65
	v_rsq_f32_e32 v64, v64
	s_nop 0
	v_pk_mul_f32 v[62:63], v[64:65], v[62:63] op_sel_hi:[0,1]
	v_pk_mul_f32 v[60:61], v[64:65], v[60:61] op_sel_hi:[0,1]
	v_pk_mul_f32 v[58:59], v[64:65], v[58:59] op_sel_hi:[0,1]
	v_pk_mul_f32 v[56:57], v[64:65], v[56:57] op_sel_hi:[0,1]
	v_pk_fma_f32 v[62:63], v[62:63], v[8:9], v[16:17]
	v_pk_fma_f32 v[60:61], v[60:61], v[10:11], v[18:19]
	v_pk_fma_f32 v[58:59], v[58:59], v[12:13], v[20:21]
	v_pk_fma_f32 v[56:57], v[56:57], v[14:15], v[22:23]
	s_waitcnt vmcnt(4)
	v_pk_fma_f32 v[42:43], v[84:85], v[42:43], v[62:63] op_sel_hi:[0,1,1]
	v_pk_fma_f32 v[38:39], v[84:85], v[38:39], v[60:61] op_sel_hi:[0,1,1]
	v_pk_fma_f32 v[34:35], v[84:85], v[34:35], v[58:59] op_sel_hi:[0,1,1]
	v_pk_fma_f32 v[32:33], v[84:85], v[32:33], v[56:57] op_sel_hi:[0,1,1]
	global_load_dword v84, v[92:93], off
	v_pk_mul_f32 v[42:43], v[42:43], v[46:47]
	v_pk_mul_f32 v[38:39], v[38:39], v[44:45]
	v_pk_mul_f32 v[34:35], v[34:35], v[40:41]
	v_pk_mul_f32 v[32:33], v[32:33], v[36:37]
	v_pk_mul_f32 v[36:37], v[42:43], v[54:55]
	v_pk_mul_f32 v[38:39], v[38:39], v[52:53]
	v_pk_mul_f32 v[34:35], v[34:35], v[50:51]
	v_pk_mul_f32 v[40:41], v[32:33], v[48:49]
	v_cvt_pk_f16_f32 v32, v36, v37
	v_cvt_pk_f16_f32 v33, v38, v39
	v_cvt_pk_f16_f32 v34, v34, v35
	v_cvt_pk_f16_f32 v35, v40, v41
	global_store_dwordx4 v[28:29], v[32:35], off
	s_cbranch_scc0 .LBB0_126
	s_waitcnt vmcnt(0)
	s_add_i32 s16, s16, s38
	s_add_i32 s3, s3, s23
	s_add_i32 s9, s9, s24
	s_cmpk_gt_i32 s16, 0x7ff
	s_cbranch_scc0 .LBB0_125
